# NSA step loops: tile-issue loop control slimmed to 3 scalar instructions on the common path (second compare, increments and re-issue branch moved out of line)
# speedup vs baseline: 1.0038x; 1.0038x over previous
.Lmore0:
	s_cmp_lt_i32 s8, s12
	s_cbranch_scc0 .LBB0_612
	s_sub_i32 s7, s7, 64
	s_sub_i32 s9, s9, 64
	s_addk_i32 s26, 0x4000
	s_add_i32 s27, s27, 0x8000
	s_branch .LBB0_602

.LBB0_610:
	s_add_i32 s8, s23, 1
	s_cmp_lt_i32 s23, s6
	s_cbranch_scc1 .Lmore0

.Lmore1:
	s_cmp_lt_i32 s23, s12
	s_cbranch_scc0 .LBB0_637
	s_sub_i32 s25, s25, 64
	s_sub_i32 s26, s26, 64
	s_addk_i32 s27, 0x4000
	s_add_i32 s28, s28, 0x8000
	s_branch .LBB0_627

.LBB0_635:
	s_add_i32 s23, s8, 1
	s_cmp_lt_i32 s8, s24
	s_cbranch_scc1 .Lmore1

.Lmore2:
	s_cmp_lt_i32 s20, s12
	s_cbranch_scc0 .LBB0_718
	s_sub_i32 s21, s21, 64
	s_sub_i32 s22, s22, 64
	s_addk_i32 s23, 0x4000
	s_add_i32 s24, s24, 0x8000
	s_branch .LBB0_708

.LBB0_716:
	s_add_i32 s20, s18, 1
	s_cmp_lt_i32 s18, s17
	s_cbranch_scc1 .Lmore2

.Lmore3:
	s_cmp_lt_i32 s18, s12
	s_cbranch_scc0 .LBB0_743
	s_sub_i32 s23, s23, 64
	s_sub_i32 s24, s24, 64
	s_addk_i32 s25, 0x4000
	s_add_i32 s26, s26, 0x8000
	s_branch .LBB0_733

.LBB0_741:
	s_add_i32 s18, s20, 1
	s_cmp_lt_i32 s20, s22
	s_cbranch_scc1 .Lmore3
